# P3 V item transposed-output loop: 16 ds_read_u16 per iteration issued together with two counted waits instead of eight serialized LDS round trips
# baseline (speedup 1.0000x reference)
.LBB0_128:
	v_add_u32_e32 v0, s9, v6
	ds_read_u16 v16, v0
	ds_read_u16 v17, v0 offset:528
	ds_read_u16 v18, v0 offset:1056
	ds_read_u16 v19, v0 offset:1584
	ds_read_u16 v20, v0 offset:4224
	ds_read_u16 v21, v0 offset:4752
	ds_read_u16 v22, v0 offset:5280
	ds_read_u16 v23, v0 offset:5808
	ds_read_u16 v24, v0 offset:32
	ds_read_u16 v25, v0 offset:560
	ds_read_u16 v26, v0 offset:1088
	ds_read_u16 v27, v0 offset:1616
	ds_read_u16 v28, v0 offset:4256
	ds_read_u16 v29, v0 offset:4784
	ds_read_u16 v30, v0 offset:5312
	v_lshl_add_u64 v[12:13], s[64:65], 0, v[2:3]
	v_lshl_add_u64 v[32:33], s[64:65], 0, v[4:5]
	s_add_i32 s9, s9, 64
	s_add_u32 s64, s64, s52
	s_addc_u32 s65, s65, s53
	s_cmpk_lg_i32 s9, 0x200
	s_waitcnt lgkmcnt(7)
	ds_read_u16 v31, v0 offset:5840
	v_lshl_or_b32 v8, v17, 16, v16
	v_lshl_or_b32 v9, v19, 16, v18
	v_lshl_or_b32 v10, v21, 16, v20
	v_lshl_or_b32 v11, v23, 16, v22
	global_store_dwordx4 v[12:13], v[8:11], off offset:-8
	s_waitcnt lgkmcnt(0)
	v_lshl_or_b32 v34, v25, 16, v24
	v_lshl_or_b32 v35, v27, 16, v26
	v_lshl_or_b32 v36, v29, 16, v28
	v_lshl_or_b32 v37, v31, 16, v30
	global_store_dwordx4 v[32:33], v[34:37], off offset:-8
	s_cbranch_scc1 .LBB0_128
	s_add_i32 s8, s8, 1
	s_add_u32 s42, s42, 0x20000
	s_addc_u32 s43, s43, 0
	s_add_u32 s48, s48, s50
	s_addc_u32 s49, s49, s51
	s_cmp_lg_u32 s8, 4
	s_barrier
	s_cbranch_scc1 .LBB0_119
	s_mov_b64 s[0:1], 0
